# attention: static s_setprio 1 on waves 0-3 instead of 4-7 (per-half A/B of the priority raise), otherwise v18
# speedup vs baseline: 1.0017x; 1.0017x over previous
; __device__ __forceinline__ int lane_id_asm() { int l; asm volatile("v_mbcnt_lo_u32_b32 %0, -1, 0\n\tv_mbcnt_hi_u32_b32 %0, -1, %0" : "=v"(l)); return l; }
; template <typename TQ>
; __device__ __forceinline__ void attn_dense_body(const TQ* __restrict__ Qb, const bf16* __restrict__ Kh, const bf16* __restrict__ Vh,
;                                                 unsigned short* __restrict__ Ob, int seq, char* lds, const int wave_s) {
;     ...
;   const int lane = lane_id_asm(), wid = wave_s, tid = wave_s * 64 + lane, r32 = lane & 31, hi = lane >> 5;
;   bf16* V_lds = (bf16*)lds; bf16* K_lds = (bf16*)(lds + 2 * SHM_V);
;   float* ws = (float*)(lds + 2 * SHM_V + 2 * SHM_K) + wid * 64; float* li_l = ws; float* al_l = ws + 32;
;   float m_reg = -1e30f, l_reg = 0; f32x16 o[4] = {}; bf16x8 qr[8];
;   const TQ* Qw = Qb + (long)(wid * QBLK + r32) * LDQ + hi * 8;
.LBB0_564:
	v_readlane_b32 s48, v254, 6
	s_cmp_ge_u32 s1, 0x20400
	s_cbranch_scc1 .Lattn_noprio
	s_setprio 1
